# score scratch stores and loads marked non-temporal (streaming cache policy) to keep K/V resident in L2
# baseline (speedup 1.0000x reference)
; DI f32x4 mfma16(bf16x8 a, bf16x8 b, f32x4 c) { return __builtin_amdgcn_mfma_f32_16x16x32_bf16(a, b, c, 0, 0, 0); }
; template <int PASS, bool DIAG>
; DI void idx_tile(const bf16x8 kf, const bf16x8 (&qf)[8], const float (&wq)[8], int kt, int lm, int lg, int tq, bool selall, u32 bA, u32 pfx,
;                  u32* hist, u32* maskw, u32* cand, u32* ccnt) {
;   const f32x4 z4 = {0.f, 0.f, 0.f, 0.f};
;   f32x4 sc = z4;
; #pragma unroll
;   for (int j = 0; j < 8; ++j) {
;     f32x4 d = mfma16(kf, qf[j], z4);
; #pragma unroll
;     for (int r = 0; r < 4; ++r) sc[r] += wq[j] * fmaxf(d[r], 0.f);
;   }
;   u32 selbits = 0u;
; #pragma unroll
;   for (int r = 0; r < 4; ++r) {
;     const int key = kt * 16 + lg * 4 + r;
;     const bool valid = !DIAG || key <= tq;
;     const u32 bits = __float_as_uint(sc[r]);
;     const u32 u = bits ^ ((u32)((int)bits >> 31) | 0x80000000u);
;     if (PASS == 0) {
;       if (valid) { const u32 bin = u >> 22; atomicAdd(&hist[lm * 512 + (bin >> 1)], 1u << ((bin & 1) * 16)); }
; template <int PASS>
; DI void idx_pass(const u16* kp, const bf16x8 (&qf)[8], const float (&wq)[8], int wave, int ntile, int lm, int lg, int tq, bool selall,
;                  u32 bA, u32 pfx, u32* hist, u32* maskw, u32* cand, u32* ccnt) {
;   auto ldk = [&](int t) { return *(const bf16x8*)(kp + (size_t)(t < ntile ? t : 0) * 512); };
;   int kt = wave;
;   bf16x8 ka = ldk(kt), kb = ldk(kt + 4);
;   for (; kt + 4 < ntile - 1; kt += 8) {
;     const bf16x8 kc = ldk(kt + 8), kd = ldk(kt + 12);
;     idx_tile<PASS, false>(ka, qf, wq, kt, lm, lg, tq, selall, bA, pfx, hist, maskw, cand, ccnt);
;     idx_tile<PASS, false>(kb, qf, wq, kt + 4, lm, lg, tq, selall, bA, pfx, hist, maskw, cand, ccnt);
;     ka = kc; kb = kd;
;   }
.LBB0_396:
	s_waitcnt vmcnt(2)
	v_mov_b64_e32 v[70:71], v[44:45]
	v_mov_b64_e32 v[68:69], v[42:43]
	v_mov_b32_e32 v46, v111
	v_add_u32_e32 v111, 8, v46
	v_cmp_le_i32_e64 s[4:5], v111, v97
	v_add_u32_e32 v110, 12, v46
	v_mfma_f32_16x16x32_bf16 v[72:75], v[68:71], v[38:41], 0
	v_cndmask_b32_e64 v42, 0, v111, s[4:5]
	v_cmp_le_i32_e64 s[4:5], v110, v97
	v_ashrrev_i32_e32 v43, 31, v42
	v_lshlrev_b64 v[42:43], 10, v[42:43]
	v_cndmask_b32_e64 v46, 0, v110, s[4:5]
	s_nop 2
	v_max_f32_e32 v72, 0, v72
	v_fma_f32 v76, v6, v72, 0
	v_max_f32_e32 v72, 0, v73
	v_fma_f32 v77, v6, v72, 0
	v_max_f32_e32 v72, 0, v74
	v_fma_f32 v78, v6, v72, 0
	v_max_f32_e32 v72, 0, v75
	v_fma_f32 v79, v6, v72, 0
	v_mfma_f32_16x16x32_bf16 v[72:75], v[68:71], v[34:37], 0
	v_ashrrev_i32_e32 v47, 31, v46
	v_lshlrev_b64 v[46:47], 10, v[46:47]
	v_lshl_add_u64 v[42:43], v[90:91], 0, v[42:43]
	v_lshl_add_u64 v[46:47], v[90:91], 0, v[46:47]
	global_load_dwordx4 v[42:45], v[42:43], off
	s_nop 2
	v_max_f32_e32 v72, 0, v72
	v_mul_f32_e32 v80, v7, v72
	v_max_f32_e32 v72, 0, v73
	v_mul_f32_e32 v81, v7, v72
	v_max_f32_e32 v72, 0, v74
	v_mul_f32_e32 v82, v7, v72
	v_max_f32_e32 v72, 0, v75
	v_mul_f32_e32 v83, v7, v72
	v_mfma_f32_16x16x32_bf16 v[72:75], v[68:71], v[30:33], 0
	v_add_f32_e64 v76, v76, v80
	v_add_f32_e64 v77, v77, v81
	global_load_dwordx4 v[46:49], v[46:47], off
	v_cmp_ge_i32_e64 s[4:5], v110, v97
	s_or_b64 s[6:7], s[4:5], s[6:7]
	s_nop 2
	v_max_f32_e32 v84, 0, v72
	v_max_f32_e32 v85, 0, v73
	v_max_f32_e32 v98, 0, v74
	v_max_f32_e32 v99, 0, v75
	v_mfma_f32_16x16x32_bf16 v[72:75], v[68:71], v[26:29], 0
	v_fma_f32 v76, v56, v84, v76
	v_fma_f32 v77, v57, v85, v77
	s_nop 5
	v_max_f32_e32 v100, 0, v72
	v_max_f32_e32 v101, 0, v73
	v_max_f32_e32 v102, 0, v74
	v_max_f32_e32 v103, 0, v75
	v_mfma_f32_16x16x32_bf16 v[72:75], v[68:71], v[22:25], 0
	v_fma_f32 v76, v58, v100, v76
	v_fma_f32 v77, v59, v101, v77
	s_nop 5
	v_max_f32_e32 v104, 0, v72
	v_max_f32_e32 v105, 0, v73
	v_max_f32_e32 v106, 0, v74
	v_max_f32_e32 v107, 0, v75
	v_mfma_f32_16x16x32_bf16 v[72:75], v[68:71], v[18:21], 0
	v_fma_f32 v76, v60, v104, v76
	v_fma_f32 v77, v61, v105, v77
	s_nop 5
	v_max_f32_e32 v112, 0, v72
	v_max_f32_e32 v113, 0, v73
	v_max_f32_e32 v114, 0, v74
	v_max_f32_e32 v115, 0, v75
	v_mfma_f32_16x16x32_bf16 v[72:75], v[68:71], v[14:17], 0
	v_fma_f32 v76, v62, v112, v76
	v_fma_f32 v77, v63, v113, v77
	v_mfma_f32_16x16x32_bf16 v[68:71], v[68:71], v[10:13], 0
	s_nop 4
	v_max_f32_e32 v72, 0, v72
	v_max_f32_e32 v73, 0, v73
	s_nop 0
	v_max_f32_e32 v68, 0, v68
	v_max_f32_e32 v69, 0, v69
	v_pk_fma_f32 v[72:73], v[64:65], v[72:73], v[76:77]
	v_pk_fma_f32 v[68:69], v[66:67], v[68:69], v[72:73]
	v_mov_b32_e32 v168, v68
	v_mov_b32_e32 v169, v69
	v_ashrrev_i32_e32 v73, 31, v68
	v_ashrrev_i32_e32 v72, 31, v69
	v_or_b32_e32 v73, 0x80000000, v73
	v_or_b32_e32 v72, 0x80000000, v72
	v_xor_b32_e32 v68, v73, v68
	v_xor_b32_e32 v69, v72, v69
	v_alignbit_b32 v73, v88, v68, 23
	v_lshrrev_b32_e32 v68, 18, v68
	v_alignbit_b32 v72, v55, v69, 23
	v_and_b32_e32 v68, 16, v68
	v_lshrrev_b32_e32 v69, 18, v69
	v_lshl_add_u32 v73, v73, 2, v96
	v_lshlrev_b32_e64 v68, v68, 1
	v_and_b32_e32 v69, 16, v69
	ds_add_u32 v73, v68
	v_lshl_add_u32 v68, v72, 2, v96
	v_lshlrev_b32_e64 v69, v69, 1
	ds_add_u32 v68, v69
	v_pk_add_f32 v[68:69], v[78:79], v[82:83]
	v_max_f32_e32 v74, 0, v74
	v_pk_fma_f32 v[68:69], v[56:57], v[98:99], v[68:69]
	v_max_f32_e32 v75, 0, v75
	v_pk_fma_f32 v[68:69], v[58:59], v[102:103], v[68:69]
	v_pk_fma_f32 v[68:69], v[60:61], v[106:107], v[68:69]
	v_pk_fma_f32 v[68:69], v[62:63], v[114:115], v[68:69]
	v_max_f32_e32 v70, 0, v70
	v_max_f32_e32 v71, 0, v71
	v_pk_fma_f32 v[68:69], v[64:65], v[74:75], v[68:69]
	s_waitcnt vmcnt(4)
; DI f32x4 mfma16(bf16x8 a, bf16x8 b, f32x4 c) { return __builtin_amdgcn_mfma_f32_16x16x32_bf16(a, b, c, 0, 0, 0); }
; template <int PASS, bool DIAG>
; DI void idx_tile(const bf16x8 kf, const bf16x8 (&qf)[8], const float (&wq)[8], int kt, int lm, int lg, int tq, bool selall, u32 bA, u32 pfx,
;                  u32* hist, u32* maskw, u32* cand, u32* ccnt) {
;   const f32x4 z4 = {0.f, 0.f, 0.f, 0.f};
;   f32x4 sc = z4;
; #pragma unroll
;   for (int j = 0; j < 8; ++j) {
;     f32x4 d = mfma16(kf, qf[j], z4);
; #pragma unroll
;     for (int r = 0; r < 4; ++r) sc[r] += wq[j] * fmaxf(d[r], 0.f);
;   }
;   u32 selbits = 0u;
; #pragma unroll
;   for (int r = 0; r < 4; ++r) {
;     const int key = kt * 16 + lg * 4 + r;
;     const bool valid = !DIAG || key <= tq;
;     const u32 bits = __float_as_uint(sc[r]);
;     const u32 u = bits ^ ((u32)((int)bits >> 31) | 0x80000000u);
;     if (PASS == 0) {
;       if (valid) { const u32 bin = u >> 22; atomicAdd(&hist[lm * 512 + (bin >> 1)], 1u << ((bin & 1) * 16)); }
; template <int PASS>
; DI void idx_pass(const u16* kp, const bf16x8 (&qf)[8], const float (&wq)[8], int wave, int ntile, int lm, int lg, int tq, bool selall,
;                  u32 bA, u32 pfx, u32* hist, u32* maskw, u32* cand, u32* ccnt) {
;   auto ldk = [&](int t) { return *(const bf16x8*)(kp + (size_t)(t < ntile ? t : 0) * 512); };
;   int kt = wave;
;   bf16x8 ka = ldk(kt), kb = ldk(kt + 4);
;   for (; kt + 4 < ntile - 1; kt += 8) {
;     const bf16x8 kc = ldk(kt + 8), kd = ldk(kt + 12);
;     idx_tile<PASS, false>(ka, qf, wq, kt, lm, lg, tq, selall, bA, pfx, hist, maskw, cand, ccnt);
;     idx_tile<PASS, false>(kb, qf, wq, kt + 4, lm, lg, tq, selall, bA, pfx, hist, maskw, cand, ccnt);
;     ka = kc; kb = kd;
;   }
	v_mfma_f32_16x16x32_bf16 v[112:115], v[50:53], v[14:17], 0
	v_fma_f32 v68, v66, v70, v68
	v_fma_f32 v69, v67, v71, v69
	v_mov_b32_e32 v170, v68
	v_mov_b32_e32 v171, v69
	v_lshl_add_u32 v172, v111, 10, v250
	global_store_dwordx4 v172, v[168:171], s[92:93] nt
	v_ashrrev_i32_e32 v71, 31, v68
	v_ashrrev_i32_e32 v70, 31, v69
	v_or_b32_e32 v71, 0x80000000, v71
	v_or_b32_e32 v70, 0x80000000, v70
	v_xor_b32_e32 v68, v71, v68
	v_xor_b32_e32 v69, v70, v69
	v_alignbit_b32 v71, v88, v68, 23
	v_lshrrev_b32_e32 v68, 18, v68
	v_alignbit_b32 v70, v55, v69, 23
	v_and_b32_e32 v68, 16, v68
	v_lshrrev_b32_e32 v69, 18, v69
	v_lshl_add_u32 v71, v71, 2, v96
	v_lshlrev_b32_e64 v68, v68, 1
	v_and_b32_e32 v69, 16, v69
	ds_add_u32 v71, v68
	v_lshl_add_u32 v68, v70, 2, v96
	v_lshlrev_b32_e64 v69, v69, 1
	ds_add_u32 v68, v69
	v_mfma_f32_16x16x32_bf16 v[68:71], v[50:53], v[38:41], 0
	s_nop 7
	v_max_f32_e32 v68, 0, v68
	v_fma_f32 v82, v6, v68, 0
	v_max_f32_e32 v68, 0, v69
	v_fma_f32 v83, v6, v68, 0
	v_max_f32_e32 v68, 0, v70
	v_fma_f32 v74, v6, v68, 0
	v_max_f32_e32 v68, 0, v71
	v_fma_f32 v75, v6, v68, 0
	v_mfma_f32_16x16x32_bf16 v[68:71], v[50:53], v[34:37], 0
	s_nop 7
	v_max_f32_e32 v68, 0, v68
	v_mul_f32_e32 v84, v7, v68
	v_max_f32_e32 v68, 0, v69
	v_mul_f32_e32 v85, v7, v68
	v_max_f32_e32 v68, 0, v70
	v_mul_f32_e32 v78, v7, v68
	v_max_f32_e32 v68, 0, v71
	v_mul_f32_e32 v79, v7, v68
	v_mfma_f32_16x16x32_bf16 v[68:71], v[50:53], v[30:33], 0
	s_nop 7
	v_max_f32_e32 v98, 0, v68
	v_max_f32_e32 v99, 0, v69
	v_max_f32_e32 v80, 0, v70
	v_max_f32_e32 v81, 0, v71
	v_mfma_f32_16x16x32_bf16 v[68:71], v[50:53], v[26:29], 0
	s_nop 7
	v_max_f32_e32 v100, 0, v68
	v_max_f32_e32 v101, 0, v69
	v_max_f32_e32 v76, 0, v70
	v_max_f32_e32 v77, 0, v71
	v_mfma_f32_16x16x32_bf16 v[68:71], v[50:53], v[22:25], 0
	s_nop 7
	v_max_f32_e32 v102, 0, v68
	v_max_f32_e32 v103, 0, v69
	v_max_f32_e32 v68, v70, v70
	v_max_f32_e32 v69, v71, v71
	v_mfma_f32_16x16x32_bf16 v[70:73], v[50:53], v[18:21], 0
	v_max_f32_e32 v68, 0, v68
	v_max_f32_e32 v69, 0, v69
	v_mfma_f32_16x16x32_bf16 v[50:53], v[50:53], v[10:13], 0
	s_nop 4
	v_max_f32_e32 v104, 0, v70
	v_max_f32_e32 v105, 0, v71
	v_max_f32_e32 v70, v72, v72
	v_max_f32_e32 v72, v112, v112
	v_max_f32_e32 v112, 0, v50
	v_max_f32_e32 v106, 0, v72
	v_max_f32_e32 v72, v113, v113
	v_max_f32_e32 v113, 0, v51
	v_max_f32_e32 v50, v52, v52
	v_max_f32_e32 v51, v53, v53
	v_pk_add_f32 v[52:53], v[82:83], v[84:85]
	v_max_f32_e32 v107, 0, v72
	v_pk_fma_f32 v[52:53], v[56:57], v[98:99], v[52:53]
	v_pk_fma_f32 v[52:53], v[58:59], v[100:101], v[52:53]
	v_max_f32_e32 v70, 0, v70
	v_pk_fma_f32 v[52:53], v[60:61], v[102:103], v[52:53]
	v_max_f32_e32 v71, 0, v73
	v_pk_fma_f32 v[52:53], v[62:63], v[104:105], v[52:53]
	v_pk_fma_f32 v[52:53], v[64:65], v[106:107], v[52:53]
	v_pk_fma_f32 v[52:53], v[66:67], v[112:113], v[52:53]
	v_mov_b32_e32 v176, v52
	v_mov_b32_e32 v177, v53
	v_max_f32_e32 v72, 0, v114
	v_ashrrev_i32_e32 v83, 31, v52
	v_ashrrev_i32_e32 v82, 31, v53
	v_or_b32_e32 v83, 0x80000000, v83
	v_or_b32_e32 v82, 0x80000000, v82
	v_xor_b32_e32 v52, v83, v52
	v_xor_b32_e32 v53, v82, v53
	v_alignbit_b32 v83, v88, v52, 23
	v_lshrrev_b32_e32 v52, 18, v52
	v_alignbit_b32 v82, v55, v53, 23
	v_and_b32_e32 v52, 16, v52
	v_lshrrev_b32_e32 v53, 18, v53
	v_lshl_add_u32 v83, v83, 2, v96
	v_lshlrev_b32_e64 v52, v52, 1
	v_and_b32_e32 v53, 16, v53
	ds_add_u32 v83, v52
	v_lshl_add_u32 v52, v82, 2, v96
	v_lshlrev_b32_e64 v53, v53, 1
	ds_add_u32 v52, v53
	v_pk_add_f32 v[52:53], v[74:75], v[78:79]
	v_max_f32_e32 v73, 0, v115
	v_pk_fma_f32 v[52:53], v[56:57], v[80:81], v[52:53]
	v_max_f32_e32 v50, 0, v50
	v_pk_fma_f32 v[52:53], v[58:59], v[76:77], v[52:53]
	v_max_f32_e32 v51, 0, v51
	v_pk_fma_f32 v[52:53], v[60:61], v[68:69], v[52:53]
	s_nop 0
	v_pk_fma_f32 v[52:53], v[62:63], v[70:71], v[52:53]
	s_nop 0
	v_pk_fma_f32 v[52:53], v[64:65], v[72:73], v[52:53]
	s_nop 0
	v_pk_fma_f32 v[50:51], v[66:67], v[50:51], v[52:53]
	v_mov_b32_e32 v178, v50
	v_mov_b32_e32 v179, v51
	global_store_dwordx4 v172, v[176:179], s[94:95] nt
	s_nop 0
	v_ashrrev_i32_e32 v53, 31, v50
	v_ashrrev_i32_e32 v52, 31, v51
	v_or_b32_e32 v53, 0x80000000, v53
	v_or_b32_e32 v52, 0x80000000, v52
	v_xor_b32_e32 v50, v53, v50
	v_xor_b32_e32 v51, v52, v51
	v_alignbit_b32 v53, v88, v50, 23
	v_lshrrev_b32_e32 v50, 18, v50
	v_alignbit_b32 v52, v55, v51, 23
	v_and_b32_e32 v50, 16, v50
	v_lshrrev_b32_e32 v51, 18, v51
	v_lshl_add_u32 v53, v53, 2, v96
	v_lshlrev_b32_e64 v50, v50, 1
	v_and_b32_e32 v51, 16, v51
	ds_add_u32 v53, v50
	v_lshl_add_u32 v50, v52, 2, v96
	v_lshlrev_b32_e64 v51, v51, 1
	ds_add_u32 v50, v51
	s_waitcnt vmcnt(2)
	v_mov_b64_e32 v[52:53], v[48:49]
	v_mov_b64_e32 v[50:51], v[46:47]
	s_andn2_b64 exec, exec, s[6:7]
	s_cbranch_execnz .LBB0_396
	s_or_b64 exec, exec, s[6:7]
	v_mov_b64_e32 v[52:53], v[48:49]
	v_mov_b64_e32 v[50:51], v[46:47]

; template <int PASS>
; DI void idx_pass(const u16* kp, const bf16x8 (&qf)[8], const float (&wq)[8], int wave, int ntile, int lm, int lg, int tq, bool selall,
;                  u32 bA, u32 pfx, u32* hist, u32* maskw, u32* cand, u32* ccnt) {
;   auto ldk = [&](int t) { return *(const bf16x8*)(kp + (size_t)(t < ntile ? t : 0) * 512); };
;   int kt = wave;
;   bf16x8 ka = ldk(kt), kb = ldk(kt + 4);
.LBB0_409:
	s_or_b64 exec, exec, s[2:3]
	s_waitcnt vmcnt(1)
	v_and_b32_e32 v43, 63, v207
	v_cmp_ne_u32_e64 s[4:5], 63, v43
	v_lshl_add_u32 v140, v109, 13, v96
	v_lshl_add_u32 v139, v141, 5, v140
	v_addc_co_u32_e64 v44, s[4:5], 0, v207, s[4:5]
	s_waitcnt lgkmcnt(0)
	s_barrier
	s_waitcnt vmcnt(0)
	s_cbranch_vccz .Lidx1_ne
	v_sub_u32_e32 v160, v97, v109
	v_subrev_u32_e32 v160, 5, v160
	v_and_b32_e32 v160, -8, v160
	v_add_u32_e32 v160, v160, v109
	v_add_u32_e32 v162, 12, v160
	v_add_u32_e32 v160, 8, v160
	v_cmp_le_i32_e64 s[4:5], v160, v97
	v_cmp_le_i32_e64 s[8:9], v162, v97
	v_mov_b32_e32 v161, 0
	v_mov_b32_e32 v163, 0
	v_cndmask_b32_e64 v160, 0, v160, s[4:5]
	v_cndmask_b32_e64 v162, 0, v162, s[8:9]
	v_lshlrev_b64 v[160:161], 10, v[160:161]
	v_lshlrev_b64 v[162:163], 10, v[162:163]
	v_lshl_add_u64 v[160:161], v[90:91], 0, v[160:161]
	v_lshl_add_u64 v[162:163], v[90:91], 0, v[162:163]
	global_load_dwordx4 v[126:129], v[160:161], off
	global_load_dwordx4 v[130:133], v[162:163], off
	v_lshl_add_u32 v134, v109, 10, v250
	s_add_u32 s92, s90, 0x1000
	s_addc_u32 s93, s91, 0
	v_readfirstlane_b32 s88, v109
	v_readfirstlane_b32 s89, v97
	global_load_dwordx4 v[110:113], v134, s[90:91] nt
	global_load_dwordx4 v[114:117], v134, s[92:93] nt
	v_add_u32_e32 v135, 0x2000, v134
	global_load_dwordx4 v[118:121], v135, s[90:91] nt
	global_load_dwordx4 v[122:125], v135, s[92:93] nt
	v_add_u32_e32 v134, 0x4000, v134

; template <int PASS, bool DIAG>
; DI void idx_tile(const bf16x8 kf, const bf16x8 (&qf)[8], const float (&wq)[8], int kt, int lm, int lg, int tq, bool selall, u32 bA, u32 pfx,
;                  u32* hist, u32* maskw, u32* cand, u32* ccnt) {
;     ...
;     } else if (PASS == 1) {
;       if (valid && (u >> 22) == bA) { const u32 bin = (u >> 12) & 1023u; atomicAdd(&hist[lm * 512 + (bin >> 1)], 1u << ((bin & 1) * 16)); }
; template <int PASS>
; DI void idx_pass(const u16* kp, const bf16x8 (&qf)[8], const float (&wq)[8], int wave, int ntile, int lm, int lg, int tq, bool selall,
;                  u32 bA, u32 pfx, u32* hist, u32* maskw, u32* cand, u32* ccnt) {
;     ...
;   for (; kt + 4 < ntile - 1; kt += 8) {
;     const bf16x8 kc = ldk(kt + 8), kd = ldk(kt + 12);
;     idx_tile<PASS, false>(ka, qf, wq, kt, lm, lg, tq, selall, bA, pfx, hist, maskw, cand, ccnt);
;     idx_tile<PASS, false>(kb, qf, wq, kt + 4, lm, lg, tq, selall, bA, pfx, hist, maskw, cand, ccnt);
;     ka = kc; kb = kd;
.Lidx1_loop:
	s_waitcnt vmcnt(2)
	v_mov_b64_e32 v[82:83], v[110:111]
	v_mov_b64_e32 v[84:85], v[112:113]
	v_mov_b64_e32 v[46:47], v[114:115]
	v_mov_b64_e32 v[48:49], v[116:117]
	global_load_dwordx4 v[110:113], v134, s[90:91] nt
	global_load_dwordx4 v[114:117], v134, s[92:93] nt
	v_add_u32_e32 v134, 0x2000, v134
	v_ashrrev_i32_e32 v58, 31, v82
	v_bitop3_b32 v54, v58, v82, s39 bitop3:0x36
	v_lshrrev_b32_e32 v58, 22, v54
	v_cmp_eq_u32_e64 s[4:5], v58, v137
	s_and_saveexec_b64 s[8:9], s[4:5]
	s_cbranch_execz .Lidx1_skip0
	v_lshrrev_b32_e32 v58, 8, v54
	v_lshrrev_b32_e32 v54, 11, v54
	v_and_b32_e32 v58, 16, v58
	v_and_b32_e32 v54, 0x7fc, v54
	v_lshlrev_b32_e64 v58, v58, 1
	v_add_u32_e32 v54, v154, v54
	ds_add_u32 v54, v58

; template <int PASS, bool DIAG>
; DI void idx_tile(const bf16x8 kf, const bf16x8 (&qf)[8], const float (&wq)[8], int kt, int lm, int lg, int tq, bool selall, u32 bA, u32 pfx,
;                  u32* hist, u32* maskw, u32* cand, u32* ccnt) {
;     ...
;     } else if (PASS == 1) {
;       if (valid && (u >> 22) == bA) { const u32 bin = (u >> 12) & 1023u; atomicAdd(&hist[lm * 512 + (bin >> 1)], 1u << ((bin & 1) * 16)); }
; template <int PASS>
; DI void idx_pass(const u16* kp, const bf16x8 (&qf)[8], const float (&wq)[8], int wave, int ntile, int lm, int lg, int tq, bool selall,
;                  u32 bA, u32 pfx, u32* hist, u32* maskw, u32* cand, u32* ccnt) {
;     ...
;   for (; kt + 4 < ntile - 1; kt += 8) {
;     const bf16x8 kc = ldk(kt + 8), kd = ldk(kt + 12);
;     idx_tile<PASS, false>(ka, qf, wq, kt, lm, lg, tq, selall, bA, pfx, hist, maskw, cand, ccnt);
;     idx_tile<PASS, false>(kb, qf, wq, kt + 4, lm, lg, tq, selall, bA, pfx, hist, maskw, cand, ccnt);
;     ka = kc; kb = kd;
.Lidx1_skip7:
	s_or_b64 exec, exec, s[8:9]
	s_add_i32 s88, s88, 8
	s_add_i32 s4, s88, 4
	s_cmp_ge_i32 s4, s89
	s_cbranch_scc1 .Lidx1_done
	s_waitcnt vmcnt(2)
	v_mov_b64_e32 v[82:83], v[118:119]
	v_mov_b64_e32 v[84:85], v[120:121]
	v_mov_b64_e32 v[46:47], v[122:123]
	v_mov_b64_e32 v[48:49], v[124:125]
	global_load_dwordx4 v[118:121], v134, s[90:91] nt
	global_load_dwordx4 v[122:125], v134, s[92:93] nt
	v_add_u32_e32 v134, 0x2000, v134
	v_ashrrev_i32_e32 v58, 31, v82
	v_bitop3_b32 v54, v58, v82, s39 bitop3:0x36
	v_lshrrev_b32_e32 v58, 22, v54
	v_cmp_eq_u32_e64 s[4:5], v58, v137
	s_and_saveexec_b64 s[8:9], s[4:5]
	s_cbranch_execz .Lidx1_skip8
	v_lshrrev_b32_e32 v58, 8, v54
	v_lshrrev_b32_e32 v54, 11, v54
	v_and_b32_e32 v58, 16, v58
	v_and_b32_e32 v54, 0x7fc, v54
	v_lshlrev_b32_e64 v58, v58, 1
	v_add_u32_e32 v54, v154, v54
	ds_add_u32 v54, v58

; template <int PASS>
; DI void idx_pass(const u16* kp, const bf16x8 (&qf)[8], const float (&wq)[8], int wave, int ntile, int lm, int lg, int tq, bool selall,
;                  u32 bA, u32 pfx, u32* hist, u32* maskw, u32* cand, u32* ccnt) {
;   auto ldk = [&](int t) { return *(const bf16x8*)(kp + (size_t)(t < ntile ? t : 0) * 512); };
;   int kt = wave;
;   bf16x8 ka = ldk(kt), kb = ldk(kt + 4);
.LBB0_641:
	s_or_b64 exec, exec, s[2:3]
	s_waitcnt lgkmcnt(0)
	s_barrier
	s_waitcnt vmcnt(0)
	s_cbranch_vccz .Lidx2_ne
	v_sub_u32_e32 v160, v97, v109
	v_subrev_u32_e32 v160, 5, v160
	v_and_b32_e32 v160, -8, v160
	v_add_u32_e32 v160, v160, v109
	v_add_u32_e32 v162, 12, v160
	v_add_u32_e32 v160, 8, v160
	v_cmp_le_i32_e64 s[4:5], v160, v97
	v_cmp_le_i32_e64 s[8:9], v162, v97
	v_mov_b32_e32 v161, 0
	v_mov_b32_e32 v163, 0
	v_cndmask_b32_e64 v160, 0, v160, s[4:5]
	v_cndmask_b32_e64 v162, 0, v162, s[8:9]
	v_lshlrev_b64 v[160:161], 10, v[160:161]
	v_lshlrev_b64 v[162:163], 10, v[162:163]
	v_lshl_add_u64 v[160:161], v[90:91], 0, v[160:161]
	v_lshl_add_u64 v[162:163], v[90:91], 0, v[162:163]
	global_load_dwordx4 v[126:129], v[160:161], off
	global_load_dwordx4 v[130:133], v[162:163], off
	v_lshl_add_u32 v134, v109, 10, v250
	s_add_u32 s92, s90, 0x1000
	s_addc_u32 s93, s91, 0
	v_readfirstlane_b32 s88, v109
	v_readfirstlane_b32 s89, v97
	global_load_dwordx4 v[110:113], v134, s[90:91] nt
	global_load_dwordx4 v[114:117], v134, s[92:93] nt
	v_add_u32_e32 v135, 0x2000, v134
	global_load_dwordx4 v[118:121], v135, s[90:91] nt
	global_load_dwordx4 v[122:125], v135, s[92:93] nt
	v_add_u32_e32 v134, 0x4000, v134

; template <int PASS, bool DIAG>
; DI void idx_tile(const bf16x8 kf, const bf16x8 (&qf)[8], const float (&wq)[8], int kt, int lm, int lg, int tq, bool selall, u32 bA, u32 pfx,
;                  u32* hist, u32* maskw, u32* cand, u32* ccnt) {
;     ...
;     } else {
;       const u32 pp = u >> 12;
;       if (valid && (selall || pp > pfx)) selbits |= 1u << r;
;       if (valid && !selall && pp == pfx) {
;         const u32 ix = atomicAdd(&ccnt[lm], 1u);
;         if (ix < 64u) { cand[(lm * 64 + ix) * 2] = u; cand[(lm * 64 + ix) * 2 + 1] = (u32)key; }
;       }
; template <int PASS>
; DI void idx_pass(const u16* kp, const bf16x8 (&qf)[8], const float (&wq)[8], int wave, int ntile, int lm, int lg, int tq, bool selall,
;                  u32 bA, u32 pfx, u32* hist, u32* maskw, u32* cand, u32* ccnt) {
;     ...
;   for (; kt + 4 < ntile - 1; kt += 8) {
;     const bf16x8 kc = ldk(kt + 8), kd = ldk(kt + 12);
;     idx_tile<PASS, false>(ka, qf, wq, kt, lm, lg, tq, selall, bA, pfx, hist, maskw, cand, ccnt);
;     idx_tile<PASS, false>(kb, qf, wq, kt + 4, lm, lg, tq, selall, bA, pfx, hist, maskw, cand, ccnt);
;     ka = kc; kb = kd;
.Lidx2_loop:
	s_waitcnt vmcnt(2)
	v_mov_b64_e32 v[82:83], v[110:111]
	v_mov_b64_e32 v[84:85], v[112:113]
	v_mov_b64_e32 v[46:47], v[114:115]
	v_mov_b64_e32 v[48:49], v[116:117]
	global_load_dwordx4 v[110:113], v134, s[90:91] nt
	global_load_dwordx4 v[114:117], v134, s[92:93] nt
	v_add_u32_e32 v134, 0x2000, v134
	v_add_u32_e32 v93, v98, v102
	v_ashrrev_i32_e32 v181, 31, v82
	v_bitop3_b32 v168, v181, v82, s39 bitop3:0x36
	v_lshrrev_b32_e32 v176, 12, v168
	v_ashrrev_i32_e32 v181, 31, v83
	v_bitop3_b32 v170, v181, v83, s39 bitop3:0x36
	v_lshrrev_b32_e32 v177, 12, v170
	v_ashrrev_i32_e32 v181, 31, v84
	v_bitop3_b32 v172, v181, v84, s39 bitop3:0x36
	v_lshrrev_b32_e32 v178, 12, v172
	v_ashrrev_i32_e32 v181, 31, v85
	v_bitop3_b32 v174, v181, v85, s39 bitop3:0x36
	v_lshrrev_b32_e32 v179, 12, v174
	v_cmp_eq_u32_e64 s[8:9], v176, v99
	v_cmp_eq_u32_e64 s[28:29], v177, v99
	v_cmp_eq_u32_e64 s[94:95], v178, v99
	v_cmp_eq_u32_e32 vcc, v179, v99
	s_or_b64 s[8:9], s[8:9], s[28:29]
	s_or_b64 s[28:29], vcc, s[94:95]
	s_or_b64 s[8:9], s[8:9], s[28:29]
	s_and_b64 s[8:9], s[8:9], s[6:7]
	s_cbranch_scc0 .Lidx2_nc0
	v_cmp_eq_u32_e32 vcc, v176, v99
	s_and_b64 s[28:29], s[6:7], vcc
	s_and_saveexec_b64 s[8:9], s[28:29]
	s_cbranch_execz .Lidx2_c0_0
	ds_add_rtn_u32 v181, v136, v203 offset:49408
	s_waitcnt lgkmcnt(0)
	v_cmp_gt_u32_e32 vcc, 64, v181
	s_and_b64 exec, exec, vcc
	v_subrev_u32_e32 v169, 64, v93
	v_lshl_add_u32 v181, v181, 3, v100
	ds_write_b64 v181, v[168:169] offset:41216

; template <int PASS, bool DIAG>
; DI void idx_tile(const bf16x8 kf, const bf16x8 (&qf)[8], const float (&wq)[8], int kt, int lm, int lg, int tq, bool selall, u32 bA, u32 pfx,
;                  u32* hist, u32* maskw, u32* cand, u32* ccnt) {
;     ...
;     } else {
;       const u32 pp = u >> 12;
;       if (valid && (selall || pp > pfx)) selbits |= 1u << r;
;       if (valid && !selall && pp == pfx) {
;         const u32 ix = atomicAdd(&ccnt[lm], 1u);
;         if (ix < 64u) { cand[(lm * 64 + ix) * 2] = u; cand[(lm * 64 + ix) * 2 + 1] = (u32)key; }
;       }
; template <int PASS>
; DI void idx_pass(const u16* kp, const bf16x8 (&qf)[8], const float (&wq)[8], int wave, int ntile, int lm, int lg, int tq, bool selall,
;                  u32 bA, u32 pfx, u32* hist, u32* maskw, u32* cand, u32* ccnt) {
;     ...
;   for (; kt + 4 < ntile - 1; kt += 8) {
;     const bf16x8 kc = ldk(kt + 8), kd = ldk(kt + 12);
;     idx_tile<PASS, false>(ka, qf, wq, kt, lm, lg, tq, selall, bA, pfx, hist, maskw, cand, ccnt);
;     idx_tile<PASS, false>(kb, qf, wq, kt + 4, lm, lg, tq, selall, bA, pfx, hist, maskw, cand, ccnt);
;     ka = kc; kb = kd;
.Lidx2_o1:
	s_or_b64 exec, exec, s[8:9]
	v_add_u32_e32 v102, 0x80, v102
	v_add_u32_e32 v109, 8, v109
	s_add_i32 s88, s88, 8
	s_add_i32 s4, s88, 4
	s_cmp_ge_i32 s4, s89
	s_cbranch_scc1 .Lidx2_done
	s_waitcnt vmcnt(2)
	v_mov_b64_e32 v[82:83], v[118:119]
	v_mov_b64_e32 v[84:85], v[120:121]
	v_mov_b64_e32 v[46:47], v[122:123]
	v_mov_b64_e32 v[48:49], v[124:125]
	global_load_dwordx4 v[118:121], v134, s[90:91] nt
	global_load_dwordx4 v[122:125], v134, s[92:93] nt
	v_add_u32_e32 v134, 0x2000, v134
	v_add_u32_e32 v93, v98, v102
	v_ashrrev_i32_e32 v181, 31, v82
	v_bitop3_b32 v168, v181, v82, s39 bitop3:0x36
	v_lshrrev_b32_e32 v176, 12, v168
	v_ashrrev_i32_e32 v181, 31, v83
	v_bitop3_b32 v170, v181, v83, s39 bitop3:0x36
	v_lshrrev_b32_e32 v177, 12, v170
	v_ashrrev_i32_e32 v181, 31, v84
	v_bitop3_b32 v172, v181, v84, s39 bitop3:0x36
	v_lshrrev_b32_e32 v178, 12, v172
	v_ashrrev_i32_e32 v181, 31, v85
	v_bitop3_b32 v174, v181, v85, s39 bitop3:0x36
	v_lshrrev_b32_e32 v179, 12, v174
	v_cmp_eq_u32_e64 s[8:9], v176, v99
	v_cmp_eq_u32_e64 s[28:29], v177, v99
	v_cmp_eq_u32_e64 s[94:95], v178, v99
	v_cmp_eq_u32_e32 vcc, v179, v99
	s_or_b64 s[8:9], s[8:9], s[28:29]
	s_or_b64 s[28:29], vcc, s[94:95]
	s_or_b64 s[8:9], s[8:9], s[28:29]
	s_and_b64 s[8:9], s[8:9], s[6:7]
	s_cbranch_scc0 .Lidx2_nc2
	v_cmp_eq_u32_e32 vcc, v176, v99
	s_and_b64 s[28:29], s[6:7], vcc
	s_and_saveexec_b64 s[8:9], s[28:29]
	s_cbranch_execz .Lidx2_c2_0
	ds_add_rtn_u32 v181, v136, v203 offset:49408
	s_waitcnt lgkmcnt(0)
	v_cmp_gt_u32_e32 vcc, 64, v181
	s_and_b64 exec, exec, vcc
	v_subrev_u32_e32 v169, 64, v93
	v_lshl_add_u32 v181, v181, 3, v100
	ds_write_b64 v181, v[168:169] offset:41216
